# conv_stream (phase 1 and in_proj ninth round): next item's loads stay in flight while the current item is finished (no full drain before reloading a register set; finish ladders count the younger stor
# speedup vs baseline: 1.0034x; 1.0034x over previous
.LBB0_151:
	s_add_u32 s4, s48, 0x4e00000
	s_addc_u32 s5, s49, 0
	s_add_u32 s6, s48, 0x4400000
	v_lshlrev_b32_e32 v37, 1, v2
	s_addc_u32 s7, s49, 0
	v_lshlrev_b32_e32 v36, 4, v2
	v_and_b32_e32 v37, 12, v37
	s_add_u32 s8, s48, 0x400000
	v_and_or_b32 v69, v36, 16, v37
	v_lshrrev_b32_e32 v73, 3, v2
	s_addc_u32 s9, s49, 0
	v_and_b32_e32 v36, 7, v1
	s_lshl_b32 s0, s12, 5
	s_lshl_b32 s1, s10, 5
	v_lshl_add_u32 v1, v36, 4, s41
	v_lshlrev_b32_e32 v72, 3, v36
	v_mul_u32_u24_e32 v36, 0x420, v36
	v_lshlrev_b32_e32 v37, 2, v73
	s_sub_i32 s0, s0, s1
	v_add3_u32 v82, s41, v36, v37
	s_add_i32 s41, s0, 0x2000
	s_lshl_b32 s0, s12, 1
	s_lshl_b32 s1, s10, 1
	s_lshl_b32 s45, s33, 5
	v_and_b32_e32 v3, 28, v68
	v_or_b32_e32 v74, 8, v73
	v_or_b32_e32 v75, 16, v73
	v_or_b32_e32 v76, 24, v73
	v_or_b32_e32 v77, 32, v73
	v_or_b32_e32 v78, 40, v73
	v_or_b32_e32 v79, 48, v73
	v_or_b32_e32 v80, 56, v73
	v_mul_u32_u24_e32 v81, 0x84, v73
	s_lshl_b32 s43, s33, 9
	s_sub_i32 s44, s0, s1
	s_add_i32 s46, s11, 0xfffff000
	s_lshl_b32 s47, s33, 4
	s_add_i32 s56, s45, 0x200
	s_lshl_b32 s57, s33, 8
	s_movk_i32 s58, 0xc0
	s_mov_b32 s11, 0
	s_mov_b32 s100, 0
	s_mov_b32 s101, 0
	s_branch .LBB0_153

.LBB0_170:
	v_add_u32_e32 v36, s10, v73
	v_add_u32_e32 v38, s10, v74
	v_add_u32_e32 v44, s10, v75
	v_add_u32_e32 v46, s10, v76
	v_add_u32_e32 v52, s10, v77
	v_add_u32_e32 v54, s10, v78
	v_add_u32_e32 v62, s10, v79
	v_add_u32_e32 v64, s10, v80
	v_add_u32_e32 v70, s20, v70
	v_mad_u64_u32 v[36:37], s[18:19], s16, v36, 0
	v_mad_u64_u32 v[38:39], s[18:19], s16, v38, 0
	v_mad_u64_u32 v[44:45], s[18:19], s16, v44, 0
	v_mad_u64_u32 v[46:47], s[18:19], s16, v46, 0
	v_mad_u64_u32 v[52:53], s[18:19], s16, v52, 0
	v_mad_u64_u32 v[54:55], s[18:19], s16, v54, 0
	v_mad_u64_u32 v[62:63], s[18:19], s16, v62, 0
	v_mad_u64_u32 v[64:65], s[16:17], s16, v64, 0
	v_lshl_add_u64 v[36:37], v[36:37], 2, s[0:1]
	v_lshlrev_b64 v[60:61], 2, v[70:71]
	v_lshl_add_u64 v[38:39], v[38:39], 2, s[0:1]
	v_lshl_add_u64 v[44:45], v[44:45], 2, s[0:1]
	v_lshl_add_u64 v[46:47], v[46:47], 2, s[0:1]
	v_lshl_add_u64 v[52:53], v[52:53], 2, s[0:1]
	v_lshl_add_u64 v[54:55], v[54:55], 2, s[0:1]
	v_lshl_add_u64 v[62:63], v[62:63], 2, s[0:1]
	v_lshl_add_u64 v[64:65], v[64:65], 2, s[0:1]
	v_lshl_add_u64 v[36:37], v[36:37], 0, v[60:61]
	v_lshl_add_u64 v[38:39], v[38:39], 0, v[60:61]
	v_lshl_add_u64 v[44:45], v[44:45], 0, v[60:61]
	v_lshl_add_u64 v[46:47], v[46:47], 0, v[60:61]
	v_lshl_add_u64 v[52:53], v[52:53], 0, v[60:61]
	v_lshl_add_u64 v[54:55], v[54:55], 0, v[60:61]
	v_lshl_add_u64 v[62:63], v[62:63], 0, v[60:61]
	v_lshl_add_u64 v[60:61], v[64:65], 0, v[60:61]
	global_load_dwordx4 v[40:43], v[36:37], off
	s_nop 0
	global_load_dwordx4 v[36:39], v[38:39], off
	s_nop 0
	global_load_dwordx4 v[48:51], v[44:45], off
	s_nop 0
	global_load_dwordx4 v[44:47], v[46:47], off
	s_nop 0
	global_load_dwordx4 v[56:59], v[52:53], off
	s_nop 0
	global_load_dwordx4 v[52:55], v[54:55], off
	s_nop 0
	global_load_dwordx4 v[64:67], v[62:63], off
	s_nop 0
	global_load_dwordx4 v[60:63], v[60:61], off
	s_mov_b32 s101, 0
	s_bitset1_b32 s100, 3

.Lcs_chkA_p:
	s_cmp_eq_u32 s100, 12
	s_cbranch_scc1 .Lcs_relA_p
	s_waitcnt vmcnt(7)
	ds_write2_b32 v70, v4, v5 offset1:1
	ds_write2_b32 v70, v6, v7 offset0:2 offset1:3
	s_waitcnt vmcnt(6)
	ds_write2_b32 v83, v8, v9 offset1:1
	v_add_u32_e32 v83, 0x428, v70
	ds_write2_b32 v83, v10, v11 offset1:1
	v_add_u32_e32 v83, 0x840, v70
	s_waitcnt vmcnt(5)
	ds_write2_b32 v83, v12, v13 offset1:1
	v_add_u32_e32 v83, 0x848, v70
	ds_write2_b32 v83, v14, v15 offset1:1
	v_add_u32_e32 v83, 0xc60, v70
	s_waitcnt vmcnt(4)
	ds_write2_b32 v83, v16, v17 offset1:1
	v_add_u32_e32 v83, 0xc68, v70
	ds_write2_b32 v83, v18, v19 offset1:1
	v_add_u32_e32 v83, 0x1080, v70
	s_waitcnt vmcnt(3)
	ds_write2_b32 v83, v20, v21 offset1:1
	v_add_u32_e32 v83, 0x1088, v70
	ds_write2_b32 v83, v22, v23 offset1:1
	v_add_u32_e32 v83, 0x14a0, v70
	s_waitcnt vmcnt(2)
	ds_write2_b32 v83, v24, v25 offset1:1
	v_add_u32_e32 v83, 0x14a8, v70
	ds_write2_b32 v83, v26, v27 offset1:1
	v_add_u32_e32 v83, 0x18c0, v70
	s_waitcnt vmcnt(1)
	ds_write2_b32 v83, v32, v33 offset1:1
	v_add_u32_e32 v83, 0x18c8, v70
	ds_write2_b32 v83, v34, v35 offset1:1
	v_add_u32_e32 v83, 0x1ce0, v70
	v_add_u32_e32 v70, 0x1ce8, v70
	s_waitcnt vmcnt(0)
	s_branch .Lcs_joinA_p
.Lcs_relA_p:
	s_waitcnt vmcnt(19)
	ds_write2_b32 v70, v4, v5 offset1:1
	ds_write2_b32 v70, v6, v7 offset0:2 offset1:3
	s_waitcnt vmcnt(18)
	ds_write2_b32 v83, v8, v9 offset1:1
	v_add_u32_e32 v83, 0x428, v70
	ds_write2_b32 v83, v10, v11 offset1:1
	v_add_u32_e32 v83, 0x840, v70
	s_waitcnt vmcnt(17)
	ds_write2_b32 v83, v12, v13 offset1:1
	v_add_u32_e32 v83, 0x848, v70
	ds_write2_b32 v83, v14, v15 offset1:1
	v_add_u32_e32 v83, 0xc60, v70
	s_waitcnt vmcnt(16)
	ds_write2_b32 v83, v16, v17 offset1:1
	v_add_u32_e32 v83, 0xc68, v70
	ds_write2_b32 v83, v18, v19 offset1:1
	v_add_u32_e32 v83, 0x1080, v70
	s_waitcnt vmcnt(15)
	ds_write2_b32 v83, v20, v21 offset1:1
	v_add_u32_e32 v83, 0x1088, v70
	ds_write2_b32 v83, v22, v23 offset1:1
	v_add_u32_e32 v83, 0x14a0, v70
	s_waitcnt vmcnt(14)
	ds_write2_b32 v83, v24, v25 offset1:1
	v_add_u32_e32 v83, 0x14a8, v70
	ds_write2_b32 v83, v26, v27 offset1:1
	v_add_u32_e32 v83, 0x18c0, v70
	s_waitcnt vmcnt(13)
	ds_write2_b32 v83, v32, v33 offset1:1
	v_add_u32_e32 v83, 0x18c8, v70
	ds_write2_b32 v83, v34, v35 offset1:1
	v_add_u32_e32 v83, 0x1ce0, v70
	v_add_u32_e32 v70, 0x1ce8, v70
	s_waitcnt vmcnt(12)
.Lcs_joinA_p:
	s_bitset1_b32 s101, 2
	ds_write2_b32 v83, v28, v29 offset1:1
	ds_write2_b32 v70, v30, v31 offset1:1
	s_waitcnt lgkmcnt(0)
	ds_read2_b32 v[88:89], v82 offset0:33 offset1:41
	ds_read2_b32 v[90:91], v82 offset1:8
	ds_read2_b32 v[92:93], v82 offset0:66 offset1:74
	ds_read2_b32 v[94:95], v82 offset0:99 offset1:107
	ds_read2_b32 v[96:97], v82 offset0:132 offset1:140
	ds_read2_b32 v[98:99], v82 offset0:165 offset1:173
	ds_read2_b32 v[100:101], v82 offset0:198 offset1:206
	ds_read2_b32 v[102:103], v82 offset0:231 offset1:239
	v_or_b32_e32 v70, s61, v73
	v_mul_hi_u32_u24_e32 v105, s0, v70
	v_mul_u32_u24_e32 v104, s0, v70
	v_lshl_add_u64 v[104:105], v[104:105], 1, s[16:17]
	s_lshl_b64 s[20:21], s[20:21], 1
	s_mov_b32 s19, s11
	v_lshl_add_u64 v[104:105], v[104:105], 0, s[20:21]
	s_lshl_b64 s[18:19], s[18:19], 1
	v_lshl_add_u64 v[104:105], v[104:105], 0, s[18:19]
	v_lshlrev_b32_e32 v70, 1, v72
	s_waitcnt lgkmcnt(6)
	v_cvt_pk_bf16_f32 v84, v90, v88
	s_waitcnt lgkmcnt(4)
	v_cvt_pk_bf16_f32 v85, v92, v94
	s_waitcnt lgkmcnt(2)
	v_cvt_pk_bf16_f32 v86, v96, v98
	s_waitcnt lgkmcnt(0)
	v_cvt_pk_bf16_f32 v87, v100, v102
	v_lshl_add_u64 v[104:105], v[104:105], 0, v[70:71]
	v_or_b32_e32 v83, s61, v74
	global_store_dwordx4 v[104:105], v[84:87], off
	v_mul_u32_u24_e32 v88, s0, v83
	s_nop 0
	v_cvt_pk_bf16_f32 v84, v91, v89
	v_mul_hi_u32_u24_e32 v89, s0, v83
	v_lshl_add_u64 v[88:89], v[88:89], 1, s[16:17]
	v_lshl_add_u64 v[88:89], v[88:89], 0, s[20:21]
	v_lshl_add_u64 v[88:89], v[88:89], 0, s[18:19]
	v_cvt_pk_bf16_f32 v85, v93, v95
	v_cvt_pk_bf16_f32 v86, v97, v99
	v_cvt_pk_bf16_f32 v87, v101, v103
	v_lshl_add_u64 v[88:89], v[88:89], 0, v[70:71]
	ds_read2_b32 v[90:91], v82 offset0:16 offset1:24
	ds_read2_b32 v[92:93], v82 offset0:49 offset1:57
	ds_read2_b32 v[94:95], v82 offset0:82 offset1:90
	ds_read2_b32 v[96:97], v82 offset0:115 offset1:123
	ds_read2_b32 v[98:99], v82 offset0:148 offset1:156
	ds_read2_b32 v[100:101], v82 offset0:181 offset1:189
	ds_read2_b32 v[102:103], v82 offset0:214 offset1:222
	ds_read2_b32 v[104:105], v82 offset0:247 offset1:255
	v_or_b32_e32 v83, s61, v75
	global_store_dwordx4 v[88:89], v[84:87], off
	v_mul_hi_u32_u24_e32 v89, s0, v83
	v_mul_u32_u24_e32 v88, s0, v83
	v_lshl_add_u64 v[88:89], v[88:89], 1, s[16:17]
	v_lshl_add_u64 v[88:89], v[88:89], 0, s[20:21]
	v_lshl_add_u64 v[88:89], v[88:89], 0, s[18:19]
	s_waitcnt lgkmcnt(6)
	v_cvt_pk_bf16_f32 v84, v90, v92
	s_waitcnt lgkmcnt(4)
	v_cvt_pk_bf16_f32 v85, v94, v96
	s_waitcnt lgkmcnt(2)
	v_cvt_pk_bf16_f32 v86, v98, v100
	s_waitcnt lgkmcnt(0)
	v_cvt_pk_bf16_f32 v87, v102, v104
	v_lshl_add_u64 v[88:89], v[88:89], 0, v[70:71]
	v_or_b32_e32 v83, s61, v76
	global_store_dwordx4 v[88:89], v[84:87], off
	v_mul_hi_u32_u24_e32 v89, s0, v83
	v_mul_u32_u24_e32 v88, s0, v83
	v_lshl_add_u64 v[88:89], v[88:89], 1, s[16:17]
	v_lshl_add_u64 v[88:89], v[88:89], 0, s[20:21]
	v_lshl_add_u64 v[88:89], v[88:89], 0, s[18:19]
	v_cvt_pk_bf16_f32 v84, v91, v93
	v_cvt_pk_bf16_f32 v85, v95, v97
	v_cvt_pk_bf16_f32 v86, v99, v101
	v_cvt_pk_bf16_f32 v87, v103, v105
	v_lshl_add_u64 v[88:89], v[88:89], 0, v[70:71]
	global_store_dwordx4 v[88:89], v[84:87], off
	s_waitcnt lgkmcnt(0)

.LBB0_201:
	v_add_u32_e32 v4, s10, v73
	v_add_u32_e32 v6, s10, v74
	v_add_u32_e32 v12, s10, v75
	v_add_u32_e32 v14, s10, v76
	v_add_u32_e32 v20, s10, v77
	v_add_u32_e32 v22, s10, v78
	v_add_u32_e32 v30, s10, v79
	v_add_u32_e32 v32, s10, v80
	v_add_u32_e32 v70, s22, v70
	v_mad_u64_u32 v[4:5], s[20:21], s18, v4, 0
	v_mad_u64_u32 v[6:7], s[20:21], s18, v6, 0
	v_mad_u64_u32 v[12:13], s[20:21], s18, v12, 0
	v_mad_u64_u32 v[14:15], s[20:21], s18, v14, 0
	v_mad_u64_u32 v[20:21], s[20:21], s18, v20, 0
	v_mad_u64_u32 v[22:23], s[20:21], s18, v22, 0
	v_mad_u64_u32 v[30:31], s[20:21], s18, v30, 0
	v_mad_u64_u32 v[32:33], s[18:19], s18, v32, 0
	v_lshl_add_u64 v[4:5], v[4:5], 2, s[0:1]
	v_lshlrev_b64 v[28:29], 2, v[70:71]
	v_lshl_add_u64 v[6:7], v[6:7], 2, s[0:1]
	v_lshl_add_u64 v[12:13], v[12:13], 2, s[0:1]
	v_lshl_add_u64 v[14:15], v[14:15], 2, s[0:1]
	v_lshl_add_u64 v[20:21], v[20:21], 2, s[0:1]
	v_lshl_add_u64 v[22:23], v[22:23], 2, s[0:1]
	v_lshl_add_u64 v[30:31], v[30:31], 2, s[0:1]
	v_lshl_add_u64 v[32:33], v[32:33], 2, s[0:1]
	v_lshl_add_u64 v[4:5], v[4:5], 0, v[28:29]
	v_lshl_add_u64 v[8:9], v[6:7], 0, v[28:29]
	v_lshl_add_u64 v[12:13], v[12:13], 0, v[28:29]
	v_lshl_add_u64 v[16:17], v[14:15], 0, v[28:29]
	v_lshl_add_u64 v[20:21], v[20:21], 0, v[28:29]
	v_lshl_add_u64 v[24:25], v[22:23], 0, v[28:29]
	v_lshl_add_u64 v[30:31], v[30:31], 0, v[28:29]
	v_lshl_add_u64 v[28:29], v[32:33], 0, v[28:29]
	global_load_dwordx4 v[4:7], v[4:5], off
	s_nop 0
	global_load_dwordx4 v[8:11], v[8:9], off
	s_nop 0
	global_load_dwordx4 v[12:15], v[12:13], off
	s_nop 0
	global_load_dwordx4 v[16:19], v[16:17], off
	s_nop 0
	global_load_dwordx4 v[20:23], v[20:21], off
	s_nop 0
	global_load_dwordx4 v[24:27], v[24:25], off
	s_nop 0
	global_load_dwordx4 v[32:35], v[30:31], off
	s_nop 0
	global_load_dwordx4 v[28:31], v[28:29], off
	s_mov_b32 s100, 0
	s_bitset1_b32 s101, 3

.Lcs_chkB_p:
	s_cmp_eq_u32 s101, 12
	s_cbranch_scc1 .Lcs_relB_p
	s_waitcnt vmcnt(7)
	ds_write2_b32 v70, v40, v41 offset1:1
	ds_write2_b32 v70, v42, v43 offset0:2 offset1:3
	s_waitcnt vmcnt(6)
	ds_write2_b32 v83, v36, v37 offset1:1
	v_add_u32_e32 v83, 0x428, v70
	ds_write2_b32 v83, v38, v39 offset1:1
	v_add_u32_e32 v83, 0x840, v70
	s_waitcnt vmcnt(5)
	ds_write2_b32 v83, v48, v49 offset1:1
	v_add_u32_e32 v83, 0x848, v70
	ds_write2_b32 v83, v50, v51 offset1:1
	v_add_u32_e32 v83, 0xc60, v70
	s_waitcnt vmcnt(4)
	ds_write2_b32 v83, v44, v45 offset1:1
	v_add_u32_e32 v83, 0xc68, v70
	ds_write2_b32 v83, v46, v47 offset1:1
	v_add_u32_e32 v83, 0x1080, v70
	s_waitcnt vmcnt(3)
	ds_write2_b32 v83, v56, v57 offset1:1
	v_add_u32_e32 v83, 0x1088, v70
	ds_write2_b32 v83, v58, v59 offset1:1
	v_add_u32_e32 v83, 0x14a0, v70
	s_waitcnt vmcnt(2)
	ds_write2_b32 v83, v52, v53 offset1:1
	v_add_u32_e32 v83, 0x14a8, v70
	ds_write2_b32 v83, v54, v55 offset1:1
	v_add_u32_e32 v83, 0x18c0, v70
	s_waitcnt vmcnt(1)
	ds_write2_b32 v83, v64, v65 offset1:1
	v_add_u32_e32 v83, 0x18c8, v70
	ds_write2_b32 v83, v66, v67 offset1:1
	v_add_u32_e32 v83, 0x1ce0, v70
	v_add_u32_e32 v70, 0x1ce8, v70
	s_waitcnt vmcnt(0)
	s_branch .Lcs_joinB_p
.Lcs_relB_p:
	s_waitcnt vmcnt(19)
	ds_write2_b32 v70, v40, v41 offset1:1
	ds_write2_b32 v70, v42, v43 offset0:2 offset1:3
	s_waitcnt vmcnt(18)
	ds_write2_b32 v83, v36, v37 offset1:1
	v_add_u32_e32 v83, 0x428, v70
	ds_write2_b32 v83, v38, v39 offset1:1
	v_add_u32_e32 v83, 0x840, v70
	s_waitcnt vmcnt(17)
	ds_write2_b32 v83, v48, v49 offset1:1
	v_add_u32_e32 v83, 0x848, v70
	ds_write2_b32 v83, v50, v51 offset1:1
	v_add_u32_e32 v83, 0xc60, v70
	s_waitcnt vmcnt(16)
	ds_write2_b32 v83, v44, v45 offset1:1
	v_add_u32_e32 v83, 0xc68, v70
	ds_write2_b32 v83, v46, v47 offset1:1
	v_add_u32_e32 v83, 0x1080, v70
	s_waitcnt vmcnt(15)
	ds_write2_b32 v83, v56, v57 offset1:1
	v_add_u32_e32 v83, 0x1088, v70
	ds_write2_b32 v83, v58, v59 offset1:1
	v_add_u32_e32 v83, 0x14a0, v70
	s_waitcnt vmcnt(14)
	ds_write2_b32 v83, v52, v53 offset1:1
	v_add_u32_e32 v83, 0x14a8, v70
	ds_write2_b32 v83, v54, v55 offset1:1
	v_add_u32_e32 v83, 0x18c0, v70
	s_waitcnt vmcnt(13)
	ds_write2_b32 v83, v64, v65 offset1:1
	v_add_u32_e32 v83, 0x18c8, v70
	ds_write2_b32 v83, v66, v67 offset1:1
	v_add_u32_e32 v83, 0x1ce0, v70
	v_add_u32_e32 v70, 0x1ce8, v70
	s_waitcnt vmcnt(12)
.Lcs_joinB_p:
	s_bitset1_b32 s100, 2
	ds_write2_b32 v83, v60, v61 offset1:1
	ds_write2_b32 v70, v62, v63 offset1:1
	s_waitcnt lgkmcnt(0)
	ds_read2_b32 v[88:89], v82 offset0:33 offset1:41
	ds_read2_b32 v[90:91], v82 offset1:8
	ds_read2_b32 v[92:93], v82 offset0:66 offset1:74
	ds_read2_b32 v[94:95], v82 offset0:99 offset1:107
	ds_read2_b32 v[96:97], v82 offset0:132 offset1:140
	ds_read2_b32 v[98:99], v82 offset0:165 offset1:173
	ds_read2_b32 v[100:101], v82 offset0:198 offset1:206
	ds_read2_b32 v[102:103], v82 offset0:231 offset1:239
	v_or_b32_e32 v70, s60, v73
	v_mul_hi_u32_u24_e32 v105, s0, v70
	v_mul_u32_u24_e32 v104, s0, v70
	v_lshl_add_u64 v[104:105], v[104:105], 1, s[12:13]
	s_lshl_b64 s[20:21], s[20:21], 1
	s_mov_b32 s19, s11
	v_lshl_add_u64 v[104:105], v[104:105], 0, s[20:21]
	s_lshl_b64 s[18:19], s[18:19], 1
	v_lshl_add_u64 v[104:105], v[104:105], 0, s[18:19]
	v_lshlrev_b32_e32 v70, 1, v72
	s_waitcnt lgkmcnt(6)
	v_cvt_pk_bf16_f32 v84, v90, v88
	s_waitcnt lgkmcnt(4)
	v_cvt_pk_bf16_f32 v85, v92, v94
	s_waitcnt lgkmcnt(2)
	v_cvt_pk_bf16_f32 v86, v96, v98
	s_waitcnt lgkmcnt(0)
	v_cvt_pk_bf16_f32 v87, v100, v102
	v_lshl_add_u64 v[104:105], v[104:105], 0, v[70:71]
	v_or_b32_e32 v83, s60, v74
	global_store_dwordx4 v[104:105], v[84:87], off
	v_mul_u32_u24_e32 v88, s0, v83
	s_nop 0
	v_cvt_pk_bf16_f32 v84, v91, v89
	v_mul_hi_u32_u24_e32 v89, s0, v83
	v_lshl_add_u64 v[88:89], v[88:89], 1, s[12:13]
	v_lshl_add_u64 v[88:89], v[88:89], 0, s[20:21]
	v_lshl_add_u64 v[88:89], v[88:89], 0, s[18:19]
	v_cvt_pk_bf16_f32 v85, v93, v95
	v_cvt_pk_bf16_f32 v86, v97, v99
	v_cvt_pk_bf16_f32 v87, v101, v103
	v_lshl_add_u64 v[88:89], v[88:89], 0, v[70:71]
	ds_read2_b32 v[90:91], v82 offset0:16 offset1:24
	ds_read2_b32 v[92:93], v82 offset0:49 offset1:57
	ds_read2_b32 v[94:95], v82 offset0:82 offset1:90
	ds_read2_b32 v[96:97], v82 offset0:115 offset1:123
	ds_read2_b32 v[98:99], v82 offset0:148 offset1:156
	ds_read2_b32 v[100:101], v82 offset0:181 offset1:189
	ds_read2_b32 v[102:103], v82 offset0:214 offset1:222
	ds_read2_b32 v[104:105], v82 offset0:247 offset1:255
	v_or_b32_e32 v83, s60, v75
	global_store_dwordx4 v[88:89], v[84:87], off
	v_mul_hi_u32_u24_e32 v89, s0, v83
	v_mul_u32_u24_e32 v88, s0, v83
	v_lshl_add_u64 v[88:89], v[88:89], 1, s[12:13]
	v_lshl_add_u64 v[88:89], v[88:89], 0, s[20:21]
	v_lshl_add_u64 v[88:89], v[88:89], 0, s[18:19]
	s_waitcnt lgkmcnt(6)
	v_cvt_pk_bf16_f32 v84, v90, v92
	s_waitcnt lgkmcnt(4)
	v_cvt_pk_bf16_f32 v85, v94, v96
	s_waitcnt lgkmcnt(2)
	v_cvt_pk_bf16_f32 v86, v98, v100
	s_waitcnt lgkmcnt(0)
	v_cvt_pk_bf16_f32 v87, v102, v104
	v_lshl_add_u64 v[88:89], v[88:89], 0, v[70:71]
	v_or_b32_e32 v83, s60, v76
	global_store_dwordx4 v[88:89], v[84:87], off
	v_mul_hi_u32_u24_e32 v89, s0, v83
	v_mul_u32_u24_e32 v88, s0, v83
	v_lshl_add_u64 v[88:89], v[88:89], 1, s[12:13]
	v_lshl_add_u64 v[88:89], v[88:89], 0, s[20:21]
	v_lshl_add_u64 v[88:89], v[88:89], 0, s[18:19]
	v_cvt_pk_bf16_f32 v84, v91, v93
	v_cvt_pk_bf16_f32 v85, v95, v97
	v_cvt_pk_bf16_f32 v86, v99, v101
	v_cvt_pk_bf16_f32 v87, v103, v105
	v_lshl_add_u64 v[88:89], v[88:89], 0, v[70:71]
	global_store_dwordx4 v[88:89], v[84:87], off
	s_waitcnt lgkmcnt(0)
	s_branch .LBB0_152

.LBB0_389:
	s_mul_i32 s7, s86, 0x2100
	s_add_i32 s42, s7, 0
	s_mov_b32 s7, s93
	s_lshl_b64 s[8:9], s[6:7], 22
	s_add_u32 s8, s52, s8
	s_addc_u32 s9, s53, s9
	s_mul_hi_u32 s11, s6, 0x1f00000
	s_add_u32 s10, s48, s0
	s_addc_u32 s11, s49, s11
	s_lshl_b64 s[12:13], s[6:7], 21
	s_add_u32 s0, s38, s12
	s_addc_u32 s13, s39, s13
	s_add_u32 s12, s0, 0x4e00000
	s_addc_u32 s13, s13, 0
	s_mul_i32 s34, s6, 0x280000
	s_mul_hi_u32 s0, s6, 0x280000
	s_add_u32 s34, s38, s34
	s_addc_u32 s0, s39, s0
	s_add_u32 s38, s34, 0x4400000
	s_addc_u32 s39, s0, 0
	s_lshl_b64 s[34:35], s[6:7], 24
	s_add_u32 s40, s43, s34
	s_addc_u32 s41, s94, s35
	s_lshl_b32 s0, s5, 11
	v_readlane_b32 s34, v253, 59
	s_add_i32 s65, s34, s0
	s_lshl_b32 s0, s5, 7
	v_readlane_b32 s34, v253, 60
	s_add_i32 s72, s34, s0
	s_lshl_b32 s0, s5, 6
	s_add_i32 s74, s86, s0
	s_mul_i32 s0, s5, 0xd0
	s_add_i32 s76, s86, s0
	s_mul_i32 s0, s5, 0x1a00
	v_readlane_b32 s34, v253, 61
	v_lshlrev_b32_e32 v32, 2, v37
	v_lshlrev_b32_e32 v34, 1, v37
	s_add_i32 s77, s34, s0
	s_mul_i32 s0, s5, 0x1a0
	v_readlane_b32 s34, v253, 62
	v_and_b32_e32 v35, 28, v32
	v_lshlrev_b32_e32 v32, 4, v37
	v_and_b32_e32 v34, 12, v34
	s_add_i32 s78, s34, s0
	s_mul_i32 s0, s5, 0x1100
	v_readlane_b32 s34, v253, 63
	v_and_or_b32 v70, v32, 16, v34
	v_lshrrev_b32_e32 v71, 3, v37
	v_and_b32_e32 v32, 7, v201
	s_add_i32 s79, s34, s0
	s_mul_i32 s0, s5, 0x110
	v_readlane_b32 s34, v254, 0
	v_lshl_add_u32 v79, v32, 4, s42
	v_lshlrev_b32_e32 v34, 3, v32
	v_mul_u32_u24_e32 v32, 0x420, v32
	v_lshlrev_b32_e32 v38, 2, v71
	s_mul_i32 s70, s5, 0x1200
	s_mul_i32 s73, s5, 0x120
	s_mul_i32 s75, s5, 0x90
	s_add_i32 s80, s34, s0
	s_mul_i32 s0, s5, 0x88
	v_or_b32_e32 v72, 8, v71
	v_or_b32_e32 v73, 16, v71
	v_or_b32_e32 v74, 24, v71
	v_or_b32_e32 v75, 32, v71
	v_or_b32_e32 v76, 40, v71
	v_or_b32_e32 v77, 48, v71
	v_or_b32_e32 v78, 56, v71
	v_mul_u32_u24_e32 v80, 0x84, v71
	v_add3_u32 v81, s42, v32, v38
	s_lshl_b32 s64, s86, 5
	s_add_i32 s70, s70, 0xffef0000
	s_lshl_b32 s71, s86, 1
	s_add_i32 s73, s73, 0xfffef000
	s_add_i32 s75, s75, 0xffff7800
	s_add_i32 s81, s86, s0
	s_mov_b32 s100, 0
	s_mov_b32 s101, 0
	s_branch .LBB0_391

.LBB0_408:
	v_add_u32_e32 v32, s52, v32
	v_lshlrev_b64 v[62:63], 2, v[32:33]
	v_add_u32_e32 v32, s0, v72
	v_mad_u64_u32 v[40:41], s[48:49], s46, v32, 0
	v_add_u32_e32 v32, s0, v73
	v_mad_u64_u32 v[46:47], s[48:49], s46, v32, 0
	v_add_u32_e32 v32, s0, v74
	v_mad_u64_u32 v[48:49], s[48:49], s46, v32, 0
	v_add_u32_e32 v32, s0, v75
	v_mad_u64_u32 v[54:55], s[48:49], s46, v32, 0
	v_add_u32_e32 v32, s0, v76
	v_mad_u64_u32 v[56:57], s[48:49], s46, v32, 0
	v_add_u32_e32 v32, s0, v77
	v_add_u32_e32 v38, s0, v71
	v_mad_u64_u32 v[64:65], s[48:49], s46, v32, 0
	v_add_u32_e32 v32, s0, v78
	v_mad_u64_u32 v[38:39], s[48:49], s46, v38, 0
	v_mad_u64_u32 v[66:67], s[46:47], s46, v32, 0
	v_lshl_add_u64 v[38:39], v[38:39], 2, s[34:35]
	v_lshl_add_u64 v[40:41], v[40:41], 2, s[34:35]
	v_lshl_add_u64 v[46:47], v[46:47], 2, s[34:35]
	v_lshl_add_u64 v[48:49], v[48:49], 2, s[34:35]
	v_lshl_add_u64 v[54:55], v[54:55], 2, s[34:35]
	v_lshl_add_u64 v[56:57], v[56:57], 2, s[34:35]
	v_lshl_add_u64 v[64:65], v[64:65], 2, s[34:35]
	v_lshl_add_u64 v[66:67], v[66:67], 2, s[34:35]
	v_lshl_add_u64 v[38:39], v[38:39], 0, v[62:63]
	v_lshl_add_u64 v[40:41], v[40:41], 0, v[62:63]
	v_lshl_add_u64 v[46:47], v[46:47], 0, v[62:63]
	v_lshl_add_u64 v[48:49], v[48:49], 0, v[62:63]
	v_lshl_add_u64 v[54:55], v[54:55], 0, v[62:63]
	v_lshl_add_u64 v[56:57], v[56:57], 0, v[62:63]
	v_lshl_add_u64 v[64:65], v[64:65], 0, v[62:63]
	v_lshl_add_u64 v[62:63], v[66:67], 0, v[62:63]
	global_load_dwordx4 v[42:45], v[38:39], off
	s_nop 0
	global_load_dwordx4 v[38:41], v[40:41], off
	s_nop 0
	global_load_dwordx4 v[50:53], v[46:47], off
	s_nop 0
	global_load_dwordx4 v[46:49], v[48:49], off
	s_nop 0
	global_load_dwordx4 v[58:61], v[54:55], off
	s_nop 0
	global_load_dwordx4 v[54:57], v[56:57], off
	s_nop 0
	global_load_dwordx4 v[66:69], v[64:65], off
	s_nop 0
	global_load_dwordx4 v[62:65], v[62:63], off
	s_mov_b32 s101, 0
	s_bitset1_b32 s100, 3

.Lcs_chkA_n:
	s_cmp_eq_u32 s100, 12
	s_cbranch_scc1 .Lcs_relA_n
	s_waitcnt vmcnt(7)
	ds_write2_b32 v32, v0, v1 offset1:1
	ds_write2_b32 v32, v2, v3 offset0:2 offset1:3
	s_waitcnt vmcnt(6)
	ds_write2_b32 v82, v4, v5 offset1:1
	v_add_u32_e32 v82, 0x428, v32
	ds_write2_b32 v82, v6, v7 offset1:1
	v_add_u32_e32 v82, 0x840, v32
	s_waitcnt vmcnt(5)
	ds_write2_b32 v82, v8, v9 offset1:1
	v_add_u32_e32 v82, 0x848, v32
	ds_write2_b32 v82, v10, v11 offset1:1
	v_add_u32_e32 v82, 0xc60, v32
	s_waitcnt vmcnt(4)
	ds_write2_b32 v82, v12, v13 offset1:1
	v_add_u32_e32 v82, 0xc68, v32
	ds_write2_b32 v82, v14, v15 offset1:1
	v_add_u32_e32 v82, 0x1080, v32
	s_waitcnt vmcnt(3)
	ds_write2_b32 v82, v16, v17 offset1:1
	v_add_u32_e32 v82, 0x1088, v32
	ds_write2_b32 v82, v18, v19 offset1:1
	v_add_u32_e32 v82, 0x14a0, v32
	s_waitcnt vmcnt(2)
	ds_write2_b32 v82, v20, v21 offset1:1
	v_add_u32_e32 v82, 0x14a8, v32
	ds_write2_b32 v82, v22, v23 offset1:1
	v_add_u32_e32 v82, 0x18c0, v32
	s_waitcnt vmcnt(1)
	ds_write2_b32 v82, v28, v29 offset1:1
	v_add_u32_e32 v82, 0x18c8, v32
	ds_write2_b32 v82, v30, v31 offset1:1
	v_add_u32_e32 v82, 0x1ce0, v32
	v_add_u32_e32 v32, 0x1ce8, v32
	s_waitcnt vmcnt(0)
	s_branch .Lcs_joinA_n
.Lcs_relA_n:
	s_waitcnt vmcnt(19)
	ds_write2_b32 v32, v0, v1 offset1:1
	ds_write2_b32 v32, v2, v3 offset0:2 offset1:3
	s_waitcnt vmcnt(18)
	ds_write2_b32 v82, v4, v5 offset1:1
	v_add_u32_e32 v82, 0x428, v32
	ds_write2_b32 v82, v6, v7 offset1:1
	v_add_u32_e32 v82, 0x840, v32
	s_waitcnt vmcnt(17)
	ds_write2_b32 v82, v8, v9 offset1:1
	v_add_u32_e32 v82, 0x848, v32
	ds_write2_b32 v82, v10, v11 offset1:1
	v_add_u32_e32 v82, 0xc60, v32
	s_waitcnt vmcnt(16)
	ds_write2_b32 v82, v12, v13 offset1:1
	v_add_u32_e32 v82, 0xc68, v32
	ds_write2_b32 v82, v14, v15 offset1:1
	v_add_u32_e32 v82, 0x1080, v32
	s_waitcnt vmcnt(15)
	ds_write2_b32 v82, v16, v17 offset1:1
	v_add_u32_e32 v82, 0x1088, v32
	ds_write2_b32 v82, v18, v19 offset1:1
	v_add_u32_e32 v82, 0x14a0, v32
	s_waitcnt vmcnt(14)
	ds_write2_b32 v82, v20, v21 offset1:1
	v_add_u32_e32 v82, 0x14a8, v32
	ds_write2_b32 v82, v22, v23 offset1:1
	v_add_u32_e32 v82, 0x18c0, v32
	s_waitcnt vmcnt(13)
	ds_write2_b32 v82, v28, v29 offset1:1
	v_add_u32_e32 v82, 0x18c8, v32
	ds_write2_b32 v82, v30, v31 offset1:1
	v_add_u32_e32 v82, 0x1ce0, v32
	v_add_u32_e32 v32, 0x1ce8, v32
	s_waitcnt vmcnt(12)
.Lcs_joinA_n:
	s_bitset1_b32 s101, 2
	ds_write2_b32 v82, v24, v25 offset1:1
	ds_write2_b32 v32, v26, v27 offset1:1
	s_waitcnt lgkmcnt(0)
	ds_read2_b32 v[86:87], v81 offset0:33 offset1:41
	ds_read2_b32 v[88:89], v81 offset1:8
	ds_read2_b32 v[90:91], v81 offset0:66 offset1:74
	ds_read2_b32 v[92:93], v81 offset0:99 offset1:107
	ds_read2_b32 v[94:95], v81 offset0:132 offset1:140
	ds_read2_b32 v[96:97], v81 offset0:165 offset1:173
	ds_read2_b32 v[98:99], v81 offset0:198 offset1:206
	ds_read2_b32 v[100:101], v81 offset0:231 offset1:239
	v_or_b32_e32 v32, s0, v71
	v_mul_hi_u32_u24_e32 v103, s34, v32
	v_mul_u32_u24_e32 v102, s34, v32
	v_lshl_add_u64 v[102:103], v[102:103], 1, s[46:47]
	s_lshl_b64 s[52:53], s[52:53], 1
	s_mov_b32 s49, s93
	v_lshl_add_u64 v[102:103], v[102:103], 0, s[52:53]
	s_lshl_b64 s[48:49], s[48:49], 1
	v_lshl_add_u64 v[102:103], v[102:103], 0, s[48:49]
	v_lshlrev_b32_e32 v32, 1, v34
	s_waitcnt lgkmcnt(6)
	v_cvt_pk_bf16_f32 v82, v88, v86
	s_waitcnt lgkmcnt(4)
	v_cvt_pk_bf16_f32 v83, v90, v92
	s_waitcnt lgkmcnt(2)
	v_cvt_pk_bf16_f32 v84, v94, v96
	s_waitcnt lgkmcnt(0)
	v_cvt_pk_bf16_f32 v85, v98, v100
	v_lshl_add_u64 v[102:103], v[102:103], 0, v[32:33]
	v_or_b32_e32 v86, s0, v72
	global_store_dwordx4 v[102:103], v[82:85], off
	s_nop 1
	v_cvt_pk_bf16_f32 v82, v89, v87
	v_mul_hi_u32_u24_e32 v87, s34, v86
	v_mul_u32_u24_e32 v86, s34, v86
	v_lshl_add_u64 v[86:87], v[86:87], 1, s[46:47]
	v_lshl_add_u64 v[86:87], v[86:87], 0, s[52:53]
	v_lshl_add_u64 v[86:87], v[86:87], 0, s[48:49]
	v_cvt_pk_bf16_f32 v83, v91, v93
	v_cvt_pk_bf16_f32 v84, v95, v97
	v_cvt_pk_bf16_f32 v85, v99, v101
	v_lshl_add_u64 v[86:87], v[86:87], 0, v[32:33]
	global_store_dwordx4 v[86:87], v[82:85], off
	ds_read2_b32 v[86:87], v81 offset0:16 offset1:24
	ds_read2_b32 v[88:89], v81 offset0:49 offset1:57
	ds_read2_b32 v[90:91], v81 offset0:82 offset1:90
	ds_read2_b32 v[92:93], v81 offset0:115 offset1:123
	ds_read2_b32 v[94:95], v81 offset0:148 offset1:156
	ds_read2_b32 v[96:97], v81 offset0:181 offset1:189
	ds_read2_b32 v[98:99], v81 offset0:214 offset1:222
	ds_read2_b32 v[100:101], v81 offset0:247 offset1:255
	s_waitcnt lgkmcnt(6)
	v_cvt_pk_bf16_f32 v82, v86, v88
	v_or_b32_e32 v86, s0, v73
	v_mul_hi_u32_u24_e32 v103, s34, v86
	v_mul_u32_u24_e32 v102, s34, v86
	v_lshl_add_u64 v[102:103], v[102:103], 1, s[46:47]
	v_lshl_add_u64 v[102:103], v[102:103], 0, s[52:53]
	v_lshl_add_u64 v[102:103], v[102:103], 0, s[48:49]
	s_waitcnt lgkmcnt(4)
	v_cvt_pk_bf16_f32 v83, v90, v92
	s_waitcnt lgkmcnt(2)
	v_cvt_pk_bf16_f32 v84, v94, v96
	s_waitcnt lgkmcnt(0)
	v_cvt_pk_bf16_f32 v85, v98, v100
	v_lshl_add_u64 v[102:103], v[102:103], 0, v[32:33]
	v_or_b32_e32 v86, s0, v74
	global_store_dwordx4 v[102:103], v[82:85], off
	s_nop 1
	v_cvt_pk_bf16_f32 v82, v87, v89
	v_mul_hi_u32_u24_e32 v87, s34, v86
	v_mul_u32_u24_e32 v86, s34, v86
	v_lshl_add_u64 v[86:87], v[86:87], 1, s[46:47]
	v_lshl_add_u64 v[86:87], v[86:87], 0, s[52:53]
	v_lshl_add_u64 v[86:87], v[86:87], 0, s[48:49]
	v_cvt_pk_bf16_f32 v83, v91, v93
	v_cvt_pk_bf16_f32 v84, v95, v97
	v_cvt_pk_bf16_f32 v85, v99, v101
	v_lshl_add_u64 v[86:87], v[86:87], 0, v[32:33]
	global_store_dwordx4 v[86:87], v[82:85], off
	s_waitcnt lgkmcnt(0)

.LBB0_439:
	v_add_u32_e32 v0, s0, v71
	v_add_u32_e32 v2, s0, v72
	v_add_u32_e32 v8, s0, v73
	v_add_u32_e32 v10, s0, v74
	v_add_u32_e32 v16, s0, v75
	v_add_u32_e32 v18, s0, v76
	v_add_u32_e32 v26, s0, v77
	v_add_u32_e32 v28, s0, v78
	v_add_u32_e32 v32, s52, v32
	v_mad_u64_u32 v[0:1], s[48:49], s46, v0, 0
	v_mad_u64_u32 v[2:3], s[48:49], s46, v2, 0
	v_mad_u64_u32 v[8:9], s[48:49], s46, v8, 0
	v_mad_u64_u32 v[10:11], s[48:49], s46, v10, 0
	v_mad_u64_u32 v[16:17], s[48:49], s46, v16, 0
	v_mad_u64_u32 v[18:19], s[48:49], s46, v18, 0
	v_mad_u64_u32 v[26:27], s[48:49], s46, v26, 0
	v_mad_u64_u32 v[28:29], s[46:47], s46, v28, 0
	v_lshl_add_u64 v[0:1], v[0:1], 2, s[34:35]
	v_lshlrev_b64 v[24:25], 2, v[32:33]
	v_lshl_add_u64 v[2:3], v[2:3], 2, s[34:35]
	v_lshl_add_u64 v[8:9], v[8:9], 2, s[34:35]
	v_lshl_add_u64 v[10:11], v[10:11], 2, s[34:35]
	v_lshl_add_u64 v[16:17], v[16:17], 2, s[34:35]
	v_lshl_add_u64 v[18:19], v[18:19], 2, s[34:35]
	v_lshl_add_u64 v[26:27], v[26:27], 2, s[34:35]
	v_lshl_add_u64 v[28:29], v[28:29], 2, s[34:35]
	v_lshl_add_u64 v[0:1], v[0:1], 0, v[24:25]
	v_lshl_add_u64 v[4:5], v[2:3], 0, v[24:25]
	v_lshl_add_u64 v[8:9], v[8:9], 0, v[24:25]
	v_lshl_add_u64 v[12:13], v[10:11], 0, v[24:25]
	v_lshl_add_u64 v[16:17], v[16:17], 0, v[24:25]
	v_lshl_add_u64 v[20:21], v[18:19], 0, v[24:25]
	v_lshl_add_u64 v[26:27], v[26:27], 0, v[24:25]
	v_lshl_add_u64 v[24:25], v[28:29], 0, v[24:25]
	global_load_dwordx4 v[0:3], v[0:1], off
	s_nop 0
	global_load_dwordx4 v[4:7], v[4:5], off
	s_nop 0
	global_load_dwordx4 v[8:11], v[8:9], off
	s_nop 0
	global_load_dwordx4 v[12:15], v[12:13], off
	s_nop 0
	global_load_dwordx4 v[16:19], v[16:17], off
	s_nop 0
	global_load_dwordx4 v[20:23], v[20:21], off
	s_nop 0
	global_load_dwordx4 v[28:31], v[26:27], off
	s_nop 0
	global_load_dwordx4 v[24:27], v[24:25], off
	s_mov_b32 s100, 0
	s_bitset1_b32 s101, 3

.Lcs_chkB_n:
	s_cmp_eq_u32 s101, 12
	s_cbranch_scc1 .Lcs_relB_n
	s_waitcnt vmcnt(7)
	ds_write2_b32 v32, v42, v43 offset1:1
	ds_write2_b32 v32, v44, v45 offset0:2 offset1:3
	s_waitcnt vmcnt(6)
	ds_write2_b32 v82, v38, v39 offset1:1
	v_add_u32_e32 v82, 0x428, v32
	ds_write2_b32 v82, v40, v41 offset1:1
	v_add_u32_e32 v82, 0x840, v32
	s_waitcnt vmcnt(5)
	ds_write2_b32 v82, v50, v51 offset1:1
	v_add_u32_e32 v82, 0x848, v32
	ds_write2_b32 v82, v52, v53 offset1:1
	v_add_u32_e32 v82, 0xc60, v32
	s_waitcnt vmcnt(4)
	ds_write2_b32 v82, v46, v47 offset1:1
	v_add_u32_e32 v82, 0xc68, v32
	ds_write2_b32 v82, v48, v49 offset1:1
	v_add_u32_e32 v82, 0x1080, v32
	s_waitcnt vmcnt(3)
	ds_write2_b32 v82, v58, v59 offset1:1
	v_add_u32_e32 v82, 0x1088, v32
	ds_write2_b32 v82, v60, v61 offset1:1
	v_add_u32_e32 v82, 0x14a0, v32
	s_waitcnt vmcnt(2)
	ds_write2_b32 v82, v54, v55 offset1:1
	v_add_u32_e32 v82, 0x14a8, v32
	ds_write2_b32 v82, v56, v57 offset1:1
	v_add_u32_e32 v82, 0x18c0, v32
	s_waitcnt vmcnt(1)
	ds_write2_b32 v82, v66, v67 offset1:1
	v_add_u32_e32 v82, 0x18c8, v32
	ds_write2_b32 v82, v68, v69 offset1:1
	v_add_u32_e32 v82, 0x1ce0, v32
	v_add_u32_e32 v32, 0x1ce8, v32
	s_waitcnt vmcnt(0)
	s_branch .Lcs_joinB_n
.Lcs_relB_n:
	s_waitcnt vmcnt(19)
	ds_write2_b32 v32, v42, v43 offset1:1
	ds_write2_b32 v32, v44, v45 offset0:2 offset1:3
	s_waitcnt vmcnt(18)
	ds_write2_b32 v82, v38, v39 offset1:1
	v_add_u32_e32 v82, 0x428, v32
	ds_write2_b32 v82, v40, v41 offset1:1
	v_add_u32_e32 v82, 0x840, v32
	s_waitcnt vmcnt(17)
	ds_write2_b32 v82, v50, v51 offset1:1
	v_add_u32_e32 v82, 0x848, v32
	ds_write2_b32 v82, v52, v53 offset1:1
	v_add_u32_e32 v82, 0xc60, v32
	s_waitcnt vmcnt(16)
	ds_write2_b32 v82, v46, v47 offset1:1
	v_add_u32_e32 v82, 0xc68, v32
	ds_write2_b32 v82, v48, v49 offset1:1
	v_add_u32_e32 v82, 0x1080, v32
	s_waitcnt vmcnt(15)
	ds_write2_b32 v82, v58, v59 offset1:1
	v_add_u32_e32 v82, 0x1088, v32
	ds_write2_b32 v82, v60, v61 offset1:1
	v_add_u32_e32 v82, 0x14a0, v32
	s_waitcnt vmcnt(14)
	ds_write2_b32 v82, v54, v55 offset1:1
	v_add_u32_e32 v82, 0x14a8, v32
	ds_write2_b32 v82, v56, v57 offset1:1
	v_add_u32_e32 v82, 0x18c0, v32
	s_waitcnt vmcnt(13)
	ds_write2_b32 v82, v66, v67 offset1:1
	v_add_u32_e32 v82, 0x18c8, v32
	ds_write2_b32 v82, v68, v69 offset1:1
	v_add_u32_e32 v82, 0x1ce0, v32
	v_add_u32_e32 v32, 0x1ce8, v32
	s_waitcnt vmcnt(12)
.Lcs_joinB_n:
	s_bitset1_b32 s100, 2
	ds_write2_b32 v82, v62, v63 offset1:1
	ds_write2_b32 v32, v64, v65 offset1:1
	s_waitcnt lgkmcnt(0)
	ds_read2_b32 v[86:87], v81 offset0:33 offset1:41
	ds_read2_b32 v[88:89], v81 offset1:8
	ds_read2_b32 v[90:91], v81 offset0:66 offset1:74
	ds_read2_b32 v[92:93], v81 offset0:99 offset1:107
	ds_read2_b32 v[94:95], v81 offset0:132 offset1:140
	ds_read2_b32 v[96:97], v81 offset0:165 offset1:173
	ds_read2_b32 v[98:99], v81 offset0:198 offset1:206
	ds_read2_b32 v[100:101], v81 offset0:231 offset1:239
	v_or_b32_e32 v32, s0, v71
	v_mul_hi_u32_u24_e32 v103, s34, v32
	v_mul_u32_u24_e32 v102, s34, v32
	v_lshl_add_u64 v[102:103], v[102:103], 1, s[42:43]
	s_lshl_b64 s[48:49], s[48:49], 1
	s_mov_b32 s47, s93
	v_lshl_add_u64 v[102:103], v[102:103], 0, s[48:49]
	s_lshl_b64 s[46:47], s[46:47], 1
	v_lshl_add_u64 v[102:103], v[102:103], 0, s[46:47]
	v_lshlrev_b32_e32 v32, 1, v34
	s_waitcnt lgkmcnt(6)
	v_cvt_pk_bf16_f32 v82, v88, v86
	s_waitcnt lgkmcnt(4)
	v_cvt_pk_bf16_f32 v83, v90, v92
	s_waitcnt lgkmcnt(2)
	v_cvt_pk_bf16_f32 v84, v94, v96
	s_waitcnt lgkmcnt(0)
	v_cvt_pk_bf16_f32 v85, v98, v100
	v_lshl_add_u64 v[102:103], v[102:103], 0, v[32:33]
	v_or_b32_e32 v86, s0, v72
	global_store_dwordx4 v[102:103], v[82:85], off
	s_nop 1
	v_cvt_pk_bf16_f32 v82, v89, v87
	v_mul_hi_u32_u24_e32 v87, s34, v86
	v_mul_u32_u24_e32 v86, s34, v86
	v_lshl_add_u64 v[86:87], v[86:87], 1, s[42:43]
	v_lshl_add_u64 v[86:87], v[86:87], 0, s[48:49]
	v_lshl_add_u64 v[86:87], v[86:87], 0, s[46:47]
	v_cvt_pk_bf16_f32 v83, v91, v93
	v_cvt_pk_bf16_f32 v84, v95, v97
	v_cvt_pk_bf16_f32 v85, v99, v101
	v_lshl_add_u64 v[86:87], v[86:87], 0, v[32:33]
	global_store_dwordx4 v[86:87], v[82:85], off
	ds_read2_b32 v[86:87], v81 offset0:16 offset1:24
	ds_read2_b32 v[88:89], v81 offset0:49 offset1:57
	ds_read2_b32 v[90:91], v81 offset0:82 offset1:90
	ds_read2_b32 v[92:93], v81 offset0:115 offset1:123
	ds_read2_b32 v[94:95], v81 offset0:148 offset1:156
	ds_read2_b32 v[96:97], v81 offset0:181 offset1:189
	ds_read2_b32 v[98:99], v81 offset0:214 offset1:222
	ds_read2_b32 v[100:101], v81 offset0:247 offset1:255
	s_waitcnt lgkmcnt(6)
	v_cvt_pk_bf16_f32 v82, v86, v88
	v_or_b32_e32 v86, s0, v73
	v_mul_hi_u32_u24_e32 v103, s34, v86
	v_mul_u32_u24_e32 v102, s34, v86
	v_lshl_add_u64 v[102:103], v[102:103], 1, s[42:43]
	v_lshl_add_u64 v[102:103], v[102:103], 0, s[48:49]
	v_lshl_add_u64 v[102:103], v[102:103], 0, s[46:47]
	s_waitcnt lgkmcnt(4)
	v_cvt_pk_bf16_f32 v83, v90, v92
	s_waitcnt lgkmcnt(2)
	v_cvt_pk_bf16_f32 v84, v94, v96
	s_waitcnt lgkmcnt(0)
	v_cvt_pk_bf16_f32 v85, v98, v100
	v_lshl_add_u64 v[102:103], v[102:103], 0, v[32:33]
	v_or_b32_e32 v86, s0, v74
	global_store_dwordx4 v[102:103], v[82:85], off
	s_nop 1
	v_cvt_pk_bf16_f32 v82, v87, v89
	v_mul_hi_u32_u24_e32 v87, s34, v86
	v_mul_u32_u24_e32 v86, s34, v86
	v_lshl_add_u64 v[86:87], v[86:87], 1, s[42:43]
	v_lshl_add_u64 v[86:87], v[86:87], 0, s[48:49]
	v_lshl_add_u64 v[86:87], v[86:87], 0, s[46:47]
	v_cvt_pk_bf16_f32 v83, v91, v93
	v_cvt_pk_bf16_f32 v84, v95, v97
	v_cvt_pk_bf16_f32 v85, v99, v101
	v_lshl_add_u64 v[86:87], v[86:87], 0, v[32:33]
	global_store_dwordx4 v[86:87], v[82:85], off
	s_waitcnt lgkmcnt(0)
	s_branch .LBB0_390
